# MLA attention unit epilogue: 8 gate loads issued up front, counted vmcnt (on v44)
# baseline (speedup 1.0000x reference)
; __device__ __forceinline__ int fresh_tid(int wid0) { int l; asm volatile("v_mbcnt_lo_u32_b32 %0, -1, 0\n\tv_mbcnt_hi_u32_b32 %0, -1, %0" : "=v"(l)); return wid0 * 64 + l; }
; __device__ __forceinline__ float bf_lo(unsigned u) { return __uint_as_float(u << 16); }
; __device__ __forceinline__ float bf_hi(unsigned u) { return __uint_as_float(u & 0xffff0000u); }
; __device__ __forceinline__ unsigned pkv(float lo, float hi) { const f32x2_t v = {lo, hi}; const bf16x2_t r = __builtin_convertvector(v, bf16x2_t); return __builtin_bit_cast(unsigned, r); }
; template <int DQK, bool MLA> ...
;     ...
;     { auto rr = __builtin_amdgcn_permlane32_swap(__float_as_uint(l_run), __float_as_uint(l_run), false, false); l_run = __uint_as_float(rr[0]) + __uint_as_float(rr[1]); }
;     const float inv = 1.f / l_run;
;     const int tid_e = fresh_tid(wid0), hi_e = (tid_e >> 5) & 1;
;     const size_t rowoff = (size_t)(wid * 32 + (tid_e & 31)) * opitch;
; #pragma unroll
;     for (int d = 0; d < 4; ++d)
; #pragma unroll
;         for (int gp = 0; gp < 2; ++gp) {
;             const int col = 32 * d + 16 * gp + 8 * hi_e;
;             const u32x4 z = *(const u32x4*)(Z + rowoff + col);
;             const auto z0 = __builtin_amdgcn_permlane32_swap(z.x, z.z, false, false), z1 = __builtin_amdgcn_permlane32_swap(z.y, z.w, false, false);
;             const int g = 2 * gp;
;             unsigned a0 = pkv(o[d][4 * g + 0] * inv * bf_lo(z0[0]), o[d][4 * g + 1] * inv * bf_hi(z0[0]));
;             unsigned a1 = pkv(o[d][4 * g + 2] * inv * bf_lo(z1[0]), o[d][4 * g + 3] * inv * bf_hi(z1[0]));
;             unsigned b0 = pkv(o[d][4 * g + 4] * inv * bf_lo(z0[1]), o[d][4 * g + 5] * inv * bf_hi(z0[1]));
;             unsigned b1 = pkv(o[d][4 * g + 6] * inv * bf_lo(z1[1]), o[d][4 * g + 7] * inv * bf_hi(z1[1]));
;             const auto w0 = __builtin_amdgcn_permlane32_swap(a0, b0, false, false), w1 = __builtin_amdgcn_permlane32_swap(a1, b1, false, false);
;             u32x4 w; w.x = w0[0]; w.y = w1[0]; w.z = w0[1]; w.w = w1[1];
;             *(u32x4*)(O + rowoff + col) = w;
;         }
.LBB0_1035:
	s_lshl_b32 s34, s44, 12
	s_add_u32 s4, s3, s34
	s_barrier
	v_mbcnt_lo_u32_b32 v68, -1, 0
	v_mbcnt_hi_u32_b32 v68, -1, v68
	v_mov_b32_e32 v65, v192
	v_and_or_b32 v64, v68, 31, s28
	s_addc_u32 s5, s2, 0
	v_lshlrev_b64 v[64:65], 12, v[64:65]
	v_lshrrev_b32_e32 v68, 1, v68
	v_lshl_add_u64 v[66:67], s[4:5], 0, v[64:65]
	v_and_b32_e32 v68, 16, v68
	v_mov_b32_e32 v69, v192
	v_lshl_add_u64 v[66:67], v[66:67], 0, v[68:69]
	global_load_dwordx4 v[100:103], v[66:67], off
	global_load_dwordx4 v[104:107], v[66:67], off offset:32
	global_load_dwordx4 v[108:111], v[66:67], off offset:64
	global_load_dwordx4 v[112:115], v[66:67], off offset:96
	global_load_dwordx4 v[116:119], v[66:67], off offset:128
	global_load_dwordx4 v[120:123], v[66:67], off offset:160
	global_load_dwordx4 v[124:127], v[66:67], off offset:192
	global_load_dwordx4 v[128:131], v[66:67], off offset:224
	v_mov_b32_e32 v74, v187
	s_nop 1
	v_permlane32_swap_b32_e32 v187, v74
	v_add_f32_e32 v74, v187, v74
	s_add_u32 s4, s56, s34
	v_div_scale_f32 v75, s[34:35], v74, v74, 1.0
	v_rcp_f32_e32 v77, v75
	s_addc_u32 s5, s57, 0
	v_lshl_add_u64 v[64:65], s[4:5], 0, v[64:65]
	v_lshl_add_u64 v[64:65], v[64:65], 0, v[68:69]
	v_fma_f32 v68, -v75, v77, 1.0
	v_div_scale_f32 v76, vcc, 1.0, v74, 1.0
	v_fmac_f32_e32 v77, v68, v77
	v_mul_f32_e32 v68, v76, v77
	v_fma_f32 v69, -v75, v68, v76
	v_fmac_f32_e32 v68, v69, v77
	v_fma_f32 v69, -v75, v68, v76
	v_div_fmas_f32 v68, v69, v77, v68
	v_div_fixup_f32 v68, v68, v74, 1.0
	v_pk_mul_f32 v[48:49], v[48:49], v[68:69] op_sel_hi:[1,0]
	v_pk_mul_f32 v[50:51], v[50:51], v[68:69] op_sel_hi:[1,0]
	v_pk_mul_f32 v[52:53], v[52:53], v[68:69] op_sel_hi:[1,0]
	v_pk_mul_f32 v[54:55], v[54:55], v[68:69] op_sel_hi:[1,0]
	s_mov_b64 s[66:67], 0
	s_and_b64 vcc, exec, s[46:47]
	s_waitcnt vmcnt(7)
	s_nop 1
	v_mov_b32_e32 v70, v100
	v_mov_b32_e32 v71, v101
	v_mov_b32_e32 v72, v102
	v_mov_b32_e32 v73, v103
	v_mov_b32_e32 v69, v72
	v_mov_b32_e32 v77, v73
	s_nop 0
	v_permlane32_swap_b32_e32 v70, v69
	v_permlane32_swap_b32_e32 v71, v77
	v_lshlrev_b32_e32 v72, 16, v70
	v_and_b32_e32 v73, 0xffff0000, v70
	v_lshlrev_b32_e32 v70, 16, v71
	v_and_b32_e32 v71, 0xffff0000, v71
	v_lshlrev_b32_e32 v74, 16, v69
	v_and_b32_e32 v75, 0xffff0000, v69
	v_lshlrev_b32_e32 v76, 16, v77
	v_and_b32_e32 v77, 0xffff0000, v77
	v_pk_mul_f32 v[48:49], v[48:49], v[72:73]
	v_pk_mul_f32 v[50:51], v[50:51], v[70:71]
	v_pk_mul_f32 v[52:53], v[52:53], v[74:75]
	v_pk_mul_f32 v[54:55], v[54:55], v[76:77]
	v_cvt_pk_bf16_f32 v48, v48, v49
	v_cvt_pk_bf16_f32 v49, v50, v51
	v_cvt_pk_bf16_f32 v50, v52, v53
	v_cvt_pk_bf16_f32 v51, v54, v55
	s_nop 0
	v_permlane32_swap_b32_e32 v48, v50
	v_permlane32_swap_b32_e32 v49, v51
	global_store_dwordx4 v[64:65], v[48:51], off
	v_pk_mul_f32 v[52:53], v[56:57], v[68:69] op_sel_hi:[1,0]
	v_pk_mul_f32 v[54:55], v[58:59], v[68:69] op_sel_hi:[1,0]
	v_pk_mul_f32 v[56:57], v[60:61], v[68:69] op_sel_hi:[1,0]
	v_pk_mul_f32 v[58:59], v[62:63], v[68:69] op_sel_hi:[1,0]
	v_pk_mul_f32 v[32:33], v[32:33], v[68:69] op_sel_hi:[1,0]
	v_pk_mul_f32 v[34:35], v[34:35], v[68:69] op_sel_hi:[1,0]
	v_pk_mul_f32 v[36:37], v[36:37], v[68:69] op_sel_hi:[1,0]
	v_pk_mul_f32 v[38:39], v[38:39], v[68:69] op_sel_hi:[1,0]
	v_pk_mul_f32 v[16:17], v[16:17], v[68:69] op_sel_hi:[1,0]
	v_pk_mul_f32 v[18:19], v[18:19], v[68:69] op_sel_hi:[1,0]
	v_pk_mul_f32 v[20:21], v[20:21], v[68:69] op_sel_hi:[1,0]
	v_pk_mul_f32 v[22:23], v[22:23], v[68:69] op_sel_hi:[1,0]
	v_pk_mul_f32 v[0:1], v[0:1], v[68:69] op_sel_hi:[1,0]
	v_pk_mul_f32 v[2:3], v[2:3], v[68:69] op_sel_hi:[1,0]
	v_pk_mul_f32 v[4:5], v[4:5], v[68:69] op_sel_hi:[1,0]
	v_pk_mul_f32 v[6:7], v[6:7], v[68:69] op_sel_hi:[1,0]
	s_waitcnt vmcnt(7)
	s_nop 1
	v_mov_b32_e32 v48, v104
	v_mov_b32_e32 v49, v105
	v_mov_b32_e32 v50, v106
	v_mov_b32_e32 v51, v107
	v_mov_b32_e32 v61, v50
	v_mov_b32_e32 v63, v51
	s_nop 0
	v_permlane32_swap_b32_e32 v48, v61
	v_permlane32_swap_b32_e32 v49, v63
	v_lshlrev_b32_e32 v50, 16, v48
	v_and_b32_e32 v51, 0xffff0000, v48
	v_lshlrev_b32_e32 v48, 16, v49
	v_and_b32_e32 v49, 0xffff0000, v49
	v_lshlrev_b32_e32 v60, 16, v61
	v_and_b32_e32 v61, 0xffff0000, v61
	v_lshlrev_b32_e32 v62, 16, v63
	v_and_b32_e32 v63, 0xffff0000, v63
	v_pk_mul_f32 v[50:51], v[52:53], v[50:51]
	v_pk_mul_f32 v[52:53], v[54:55], v[48:49]
	v_pk_mul_f32 v[54:55], v[56:57], v[60:61]
	v_pk_mul_f32 v[56:57], v[58:59], v[62:63]
	v_cvt_pk_bf16_f32 v48, v50, v51
	v_cvt_pk_bf16_f32 v49, v52, v53
	v_cvt_pk_bf16_f32 v50, v54, v55
	v_cvt_pk_bf16_f32 v51, v56, v57
	s_nop 0
	v_permlane32_swap_b32_e32 v48, v50
	v_permlane32_swap_b32_e32 v49, v51
	global_store_dwordx4 v[64:65], v[48:51], off offset:32
	s_waitcnt vmcnt(7)
	s_nop 1
	v_mov_b32_e32 v48, v108
	v_mov_b32_e32 v49, v109
	v_mov_b32_e32 v50, v110
	v_mov_b32_e32 v51, v111
	v_mov_b32_e32 v53, v50
	v_mov_b32_e32 v55, v51
	s_nop 0
	v_permlane32_swap_b32_e32 v48, v53
	v_permlane32_swap_b32_e32 v49, v55
	v_lshlrev_b32_e32 v50, 16, v48
	v_and_b32_e32 v51, 0xffff0000, v48
	v_lshlrev_b32_e32 v48, 16, v49
	v_and_b32_e32 v49, 0xffff0000, v49
	v_lshlrev_b32_e32 v52, 16, v53
	v_and_b32_e32 v53, 0xffff0000, v53
	v_lshlrev_b32_e32 v54, 16, v55
	v_and_b32_e32 v55, 0xffff0000, v55
	v_pk_mul_f32 v[32:33], v[32:33], v[50:51]
	v_pk_mul_f32 v[34:35], v[34:35], v[48:49]
	v_pk_mul_f32 v[36:37], v[36:37], v[52:53]
	v_pk_mul_f32 v[38:39], v[38:39], v[54:55]
	v_cvt_pk_bf16_f32 v32, v32, v33
	v_cvt_pk_bf16_f32 v33, v34, v35
	v_cvt_pk_bf16_f32 v34, v36, v37
	v_cvt_pk_bf16_f32 v35, v38, v39
	s_nop 0
	v_permlane32_swap_b32_e32 v32, v34
	v_permlane32_swap_b32_e32 v33, v35
	global_store_dwordx4 v[64:65], v[32:35], off offset:64
	v_pk_mul_f32 v[36:37], v[40:41], v[68:69] op_sel_hi:[1,0]
	v_pk_mul_f32 v[38:39], v[42:43], v[68:69] op_sel_hi:[1,0]
	v_pk_mul_f32 v[40:41], v[44:45], v[68:69] op_sel_hi:[1,0]
	v_pk_mul_f32 v[42:43], v[46:47], v[68:69] op_sel_hi:[1,0]
	s_waitcnt vmcnt(7)
; __device__ __forceinline__ float bf_lo(unsigned u) { return __uint_as_float(u << 16); }
; __device__ __forceinline__ float bf_hi(unsigned u) { return __uint_as_float(u & 0xffff0000u); }
; __device__ __forceinline__ unsigned pkv(float lo, float hi) { const f32x2_t v = {lo, hi}; const bf16x2_t r = __builtin_convertvector(v, bf16x2_t); return __builtin_bit_cast(unsigned, r); }
; template <int DQK, bool MLA> ...
;     ...
; #pragma unroll
;     for (int d = 0; d < 4; ++d)
; #pragma unroll
;         for (int gp = 0; gp < 2; ++gp) {
;             const int col = 32 * d + 16 * gp + 8 * hi_e;
;             const u32x4 z = *(const u32x4*)(Z + rowoff + col);
;             const auto z0 = __builtin_amdgcn_permlane32_swap(z.x, z.z, false, false), z1 = __builtin_amdgcn_permlane32_swap(z.y, z.w, false, false);
;             const int g = 2 * gp;
;             unsigned a0 = pkv(o[d][4 * g + 0] * inv * bf_lo(z0[0]), o[d][4 * g + 1] * inv * bf_hi(z0[0]));
;             unsigned a1 = pkv(o[d][4 * g + 2] * inv * bf_lo(z1[0]), o[d][4 * g + 3] * inv * bf_hi(z1[0]));
;             unsigned b0 = pkv(o[d][4 * g + 4] * inv * bf_lo(z0[1]), o[d][4 * g + 5] * inv * bf_hi(z0[1]));
;             unsigned b1 = pkv(o[d][4 * g + 6] * inv * bf_lo(z1[1]), o[d][4 * g + 7] * inv * bf_hi(z1[1]));
;             const auto w0 = __builtin_amdgcn_permlane32_swap(a0, b0, false, false), w1 = __builtin_amdgcn_permlane32_swap(a1, b1, false, false);
;             u32x4 w; w.x = w0[0]; w.y = w1[0]; w.z = w0[1]; w.w = w1[1];
;             *(u32x4*)(O + rowoff + col) = w;
;         }
	s_nop 1
	v_mov_b32_e32 v32, v112
	v_mov_b32_e32 v33, v113
	v_mov_b32_e32 v34, v114
	v_mov_b32_e32 v35, v115
	v_mov_b32_e32 v45, v34
	v_mov_b32_e32 v47, v35
	s_nop 0
	v_permlane32_swap_b32_e32 v32, v45
	v_permlane32_swap_b32_e32 v33, v47
	v_lshlrev_b32_e32 v34, 16, v32
	v_and_b32_e32 v35, 0xffff0000, v32
	v_lshlrev_b32_e32 v32, 16, v33
	v_and_b32_e32 v33, 0xffff0000, v33
	v_lshlrev_b32_e32 v44, 16, v45
	v_and_b32_e32 v45, 0xffff0000, v45
	v_lshlrev_b32_e32 v46, 16, v47
	v_and_b32_e32 v47, 0xffff0000, v47
	v_pk_mul_f32 v[34:35], v[36:37], v[34:35]
	v_pk_mul_f32 v[36:37], v[38:39], v[32:33]
	v_pk_mul_f32 v[38:39], v[40:41], v[44:45]
	v_pk_mul_f32 v[40:41], v[42:43], v[46:47]
	v_cvt_pk_bf16_f32 v32, v34, v35
	v_cvt_pk_bf16_f32 v33, v36, v37
	v_cvt_pk_bf16_f32 v34, v38, v39
	v_cvt_pk_bf16_f32 v35, v40, v41
	s_nop 0
	v_permlane32_swap_b32_e32 v32, v34
	v_permlane32_swap_b32_e32 v33, v35
	global_store_dwordx4 v[64:65], v[32:35], off offset:96
	s_waitcnt vmcnt(7)
	s_nop 1
	v_mov_b32_e32 v32, v116
	v_mov_b32_e32 v33, v117
	v_mov_b32_e32 v34, v118
	v_mov_b32_e32 v35, v119
	v_mov_b32_e32 v37, v34
	v_mov_b32_e32 v39, v35
	s_nop 0
	v_permlane32_swap_b32_e32 v32, v37
	v_permlane32_swap_b32_e32 v33, v39
	v_lshlrev_b32_e32 v34, 16, v32
	v_and_b32_e32 v35, 0xffff0000, v32
	v_lshlrev_b32_e32 v32, 16, v33
	v_and_b32_e32 v33, 0xffff0000, v33
	v_lshlrev_b32_e32 v36, 16, v37
	v_and_b32_e32 v37, 0xffff0000, v37
	v_lshlrev_b32_e32 v38, 16, v39
	v_and_b32_e32 v39, 0xffff0000, v39
	v_pk_mul_f32 v[16:17], v[16:17], v[34:35]
	v_pk_mul_f32 v[18:19], v[18:19], v[32:33]
	v_pk_mul_f32 v[20:21], v[20:21], v[36:37]
	v_pk_mul_f32 v[22:23], v[22:23], v[38:39]
	v_cvt_pk_bf16_f32 v16, v16, v17
	v_cvt_pk_bf16_f32 v17, v18, v19
	v_cvt_pk_bf16_f32 v18, v20, v21
	v_cvt_pk_bf16_f32 v19, v22, v23
	s_nop 0
	v_permlane32_swap_b32_e32 v16, v18
	v_permlane32_swap_b32_e32 v17, v19
	global_store_dwordx4 v[64:65], v[16:19], off offset:128
	v_pk_mul_f32 v[20:21], v[24:25], v[68:69] op_sel_hi:[1,0]
	v_pk_mul_f32 v[22:23], v[26:27], v[68:69] op_sel_hi:[1,0]
	v_pk_mul_f32 v[24:25], v[28:29], v[68:69] op_sel_hi:[1,0]
	v_pk_mul_f32 v[26:27], v[30:31], v[68:69] op_sel_hi:[1,0]
	s_waitcnt vmcnt(7)
	s_nop 1
	v_mov_b32_e32 v16, v120
	v_mov_b32_e32 v17, v121
	v_mov_b32_e32 v18, v122
	v_mov_b32_e32 v19, v123
	v_mov_b32_e32 v29, v18
	v_mov_b32_e32 v31, v19
	s_nop 0
	v_permlane32_swap_b32_e32 v16, v29
	v_permlane32_swap_b32_e32 v17, v31
	v_lshlrev_b32_e32 v18, 16, v16
	v_and_b32_e32 v19, 0xffff0000, v16
	v_lshlrev_b32_e32 v16, 16, v17
	v_and_b32_e32 v17, 0xffff0000, v17
	v_lshlrev_b32_e32 v28, 16, v29
	v_and_b32_e32 v29, 0xffff0000, v29
	v_lshlrev_b32_e32 v30, 16, v31
	v_and_b32_e32 v31, 0xffff0000, v31
	v_pk_mul_f32 v[18:19], v[20:21], v[18:19]
	v_pk_mul_f32 v[20:21], v[22:23], v[16:17]
	v_pk_mul_f32 v[22:23], v[24:25], v[28:29]
	v_pk_mul_f32 v[24:25], v[26:27], v[30:31]
	v_cvt_pk_bf16_f32 v16, v18, v19
	v_cvt_pk_bf16_f32 v17, v20, v21
	v_cvt_pk_bf16_f32 v18, v22, v23
	v_cvt_pk_bf16_f32 v19, v24, v25
	s_nop 0
	v_permlane32_swap_b32_e32 v16, v18
	v_permlane32_swap_b32_e32 v17, v19
	global_store_dwordx4 v[64:65], v[16:19], off offset:160
	s_waitcnt vmcnt(7)
	s_nop 1
	v_mov_b32_e32 v16, v124
	v_mov_b32_e32 v17, v125
	v_mov_b32_e32 v18, v126
	v_mov_b32_e32 v19, v127
	v_mov_b32_e32 v21, v18
	v_mov_b32_e32 v23, v19
	s_nop 0
	v_permlane32_swap_b32_e32 v16, v21
	v_permlane32_swap_b32_e32 v17, v23
	v_lshlrev_b32_e32 v18, 16, v16
	v_and_b32_e32 v19, 0xffff0000, v16
	v_lshlrev_b32_e32 v16, 16, v17
	v_and_b32_e32 v17, 0xffff0000, v17
	v_lshlrev_b32_e32 v20, 16, v21
	v_and_b32_e32 v21, 0xffff0000, v21
	v_lshlrev_b32_e32 v22, 16, v23
	v_and_b32_e32 v23, 0xffff0000, v23
	v_pk_mul_f32 v[0:1], v[0:1], v[18:19]
	v_pk_mul_f32 v[2:3], v[2:3], v[16:17]
	v_pk_mul_f32 v[4:5], v[4:5], v[20:21]
	v_pk_mul_f32 v[6:7], v[6:7], v[22:23]
	v_cvt_pk_bf16_f32 v0, v0, v1
	v_cvt_pk_bf16_f32 v1, v2, v3
	v_cvt_pk_bf16_f32 v2, v4, v5
	v_cvt_pk_bf16_f32 v3, v6, v7
	s_nop 0
	v_permlane32_swap_b32_e32 v0, v2
	v_permlane32_swap_b32_e32 v1, v3
	global_store_dwordx4 v[64:65], v[0:3], off offset:192
	v_pk_mul_f32 v[4:5], v[8:9], v[68:69] op_sel_hi:[1,0]
	v_pk_mul_f32 v[6:7], v[10:11], v[68:69] op_sel_hi:[1,0]
	v_pk_mul_f32 v[8:9], v[12:13], v[68:69] op_sel_hi:[1,0]
	v_pk_mul_f32 v[10:11], v[14:15], v[68:69] op_sel_hi:[1,0]
	s_waitcnt vmcnt(7)
	s_nop 1
	v_mov_b32_e32 v0, v128
	v_mov_b32_e32 v1, v129
	v_mov_b32_e32 v2, v130
	v_mov_b32_e32 v3, v131
	v_mov_b32_e32 v13, v2
	v_mov_b32_e32 v15, v3
	s_nop 0
	v_permlane32_swap_b32_e32 v0, v13
	v_permlane32_swap_b32_e32 v1, v15
	v_lshlrev_b32_e32 v2, 16, v0
	v_and_b32_e32 v3, 0xffff0000, v0
	v_lshlrev_b32_e32 v0, 16, v1
	v_and_b32_e32 v1, 0xffff0000, v1
	v_lshlrev_b32_e32 v12, 16, v13
	v_and_b32_e32 v13, 0xffff0000, v13
	v_lshlrev_b32_e32 v14, 16, v15
	v_and_b32_e32 v15, 0xffff0000, v15
	v_pk_mul_f32 v[2:3], v[4:5], v[2:3]
	v_pk_mul_f32 v[4:5], v[6:7], v[0:1]
	v_pk_mul_f32 v[6:7], v[8:9], v[12:13]
	v_pk_mul_f32 v[8:9], v[10:11], v[14:15]
	v_cvt_pk_bf16_f32 v0, v2, v3
	v_cvt_pk_bf16_f32 v1, v4, v5
	v_cvt_pk_bf16_f32 v2, v6, v7
	v_cvt_pk_bf16_f32 v3, v8, v9
	s_nop 0
	v_permlane32_swap_b32_e32 v0, v2
	v_permlane32_swap_b32_e32 v1, v3
	global_store_dwordx4 v[64:65], v[0:3], off offset:224
	s_cbranch_vccnz .LBB0_1033
